# diff loop top: next-tile loads issued right after each staging ds_write (constant vmcnt ladder)
# speedup vs baseline: 1.0328x; 1.0070x over previous
.LBB0_869:
	s_mul_i32 s43, s42, 0x8c00
	s_add_i32 s0, s34, s6
	s_sub_i32 s44, s0, 64
	s_cmp_eq_u32 s44, 0
	s_cbranch_scc1 .Ldiff_top_last
	v_add3_u32 v0, s43, v224, v225
	v_lshl_add_u64 v[2:3], v[176:177], 0, v[172:173]
	s_waitcnt vmcnt(7)
	ds_write_b128 v0, v[128:131]
	global_load_dwordx4 v[128:131], v[2:3], off
	v_add_u32_e32 v0, s43, v226
	v_add3_u32 v0, v0, v227, s93
	v_lshl_add_u64 v[2:3], v[184:185], 0, v[174:175]
	s_waitcnt vmcnt(7)
	ds_write2_b64 v0, v[132:133], v[134:135] offset1:1
	global_load_dwordx4 v[132:135], v[2:3], off
	v_add3_u32 v0, s43, v162, v225
	v_lshl_add_u64 v[2:3], v[190:191], 0, v[172:173]
	s_waitcnt vmcnt(7)
	ds_write_b128 v0, v[136:139]
	global_load_dwordx4 v[136:139], v[2:3], off
	v_add_u32_e32 v0, s43, v219
	v_add3_u32 v0, v0, v227, s93
	v_lshl_add_u64 v[2:3], v[182:183], 0, v[174:175]
	s_waitcnt vmcnt(7)
	ds_write2_b64 v0, v[140:141], v[142:143] offset1:1
	global_load_dwordx4 v[140:143], v[2:3], off
	v_add3_u32 v0, s43, v220, v225
	v_lshl_add_u64 v[2:3], v[188:189], 0, v[172:173]
	s_waitcnt vmcnt(7)
	ds_write_b128 v0, v[144:147]
	global_load_dwordx4 v[144:147], v[2:3], off
	v_add_u32_e32 v0, s43, v221
	v_add3_u32 v0, v0, v227, s93
	v_lshl_add_u64 v[2:3], v[180:181], 0, v[174:175]
	s_waitcnt vmcnt(7)
	ds_write2_b64 v0, v[148:149], v[150:151] offset1:1
	global_load_dwordx4 v[148:151], v[2:3], off
	v_add3_u32 v0, s43, v222, v225
	v_lshl_add_u64 v[2:3], v[186:187], 0, v[172:173]
	s_waitcnt vmcnt(7)
	ds_write_b128 v0, v[152:155]
	global_load_dwordx4 v[152:155], v[2:3], off
	v_add_u32_e32 v0, s43, v223
	v_add3_u32 v0, v0, v227, s93
	v_lshl_add_u64 v[2:3], v[178:179], 0, v[174:175]
	s_waitcnt vmcnt(7)
	ds_write2_b64 v0, v[156:157], v[158:159] offset1:1
	global_load_dwordx4 v[156:159], v[2:3], off
	s_branch .LBB0_871
.Ldiff_top_last:
	v_add3_u32 v0, s43, v224, v225
	s_waitcnt vmcnt(7)
	ds_write_b128 v0, v[128:131]
	v_add_u32_e32 v0, s43, v226
	v_add3_u32 v0, v0, v227, s93
	s_waitcnt vmcnt(6)
	ds_write2_b64 v0, v[132:133], v[134:135] offset1:1
	v_add3_u32 v0, s43, v162, v225
	s_waitcnt vmcnt(5)
	ds_write_b128 v0, v[136:139]
	v_add_u32_e32 v0, s43, v219
	v_add3_u32 v0, v0, v227, s93
	s_waitcnt vmcnt(4)
	ds_write2_b64 v0, v[140:141], v[142:143] offset1:1
	v_add3_u32 v0, s43, v220, v225
	s_waitcnt vmcnt(3)
	ds_write_b128 v0, v[144:147]
	v_add_u32_e32 v0, s43, v221
	v_add3_u32 v0, v0, v227, s93
	s_waitcnt vmcnt(2)
	ds_write2_b64 v0, v[148:149], v[150:151] offset1:1
	v_add3_u32 v0, s43, v222, v225
	s_waitcnt vmcnt(1)
	ds_write_b128 v0, v[152:155]
	v_add_u32_e32 v0, s43, v223
	v_add3_u32 v0, v0, v227, s93
	s_waitcnt vmcnt(0)
	ds_write2_b64 v0, v[156:157], v[158:159] offset1:1
